# SwiGLU GEMM phases: short start stagger (s_sleep 0x30, about 1.5 us) for odd in-XCD blocks, on top of v74
# speedup vs baseline: 1.0034x; 1.0034x over previous
.LBB0_139:
	s_and_b64 vcc, exec, s[8:9]
	s_cbranch_vccz .LBB0_152
	v_readlane_b32 s98, v255, 18
	s_bitcmp0_b32 s98, 3
	s_cbranch_scc1 .Lstag_skip_sw
	s_sleep 0x30
